# stack28 + P7 row loop: next row's first four input loads prefetched mid-row, loop top only moves them into place, waits recounted
# baseline (speedup 1.0000x reference)
.LBB0_1035:
	s_cmp_lt_i32 s92, 8
	s_cselect_b64 s[4:5], -1, 0
	s_and_b64 s[4:5], s[4:5], s[2:3]
	s_andn2_b64 vcc, exec, s[4:5]
	s_cbranch_vccnz .LBB0_1039
	s_mov_b32 s2, 0
	s_ashr_i32 s3, s2, 31
	s_add_u32 s6, s0, s2
	s_addc_u32 s7, s1, s3
	s_waitcnt lgkmcnt(0)
	s_load_dwordx8 s[12:19], s[6:7], 0x38
	v_mbcnt_lo_u32_b32 v0, -1, 0
	v_mbcnt_hi_u32_b32 v1, -1, v0
	v_and_b32_e32 v0, 63, v1
	v_lshlrev_b32_e32 v2, 2, v0
	s_waitcnt lgkmcnt(0)
	global_load_dword v3, v2, s[12:13]
	global_load_dword v4, v2, s[14:15]
	global_load_dword v5, v2, s[12:13] offset:256
	global_load_dword v6, v2, s[14:15] offset:256
	global_load_dword v7, v2, s[16:17] offset:256
	global_load_dword v8, v2, s[18:19] offset:256
	global_load_dword v9, v2, s[16:17]
	global_load_dword v11, v2, s[18:19]
	v_and_b32_e32 v2, 64, v1
	v_xor_b32_e32 v10, 1, v1
	v_add_u32_e32 v2, 64, v2
	v_cmp_lt_i32_e32 vcc, v10, v2
	v_xor_b32_e32 v12, 2, v1
	v_xor_b32_e32 v13, 4, v1
	v_cndmask_b32_e32 v10, v1, v10, vcc
	v_lshlrev_b32_e32 v10, 2, v10
	v_cmp_lt_i32_e32 vcc, v12, v2
	v_xor_b32_e32 v14, 8, v1
	v_xor_b32_e32 v15, 16, v1
	v_xor_b32_e32 v16, 32, v1
	s_cmpk_gt_i32 s20, 0x3fff
	s_waitcnt vmcnt(0)
	v_mul_f32_e32 v5, v5, v6
	v_fmac_f32_e32 v5, v3, v4
	v_mul_f32_e32 v6, v7, v8
	ds_bpermute_b32 v3, v10, v5
	v_fmac_f32_e32 v6, v9, v11
	ds_bpermute_b32 v4, v10, v6
	v_cndmask_b32_e32 v7, v1, v12, vcc
	v_lshlrev_b32_e32 v11, 2, v7
	s_waitcnt lgkmcnt(1)
	v_add_f32_e32 v3, v5, v3
	ds_bpermute_b32 v5, v11, v3
	s_waitcnt lgkmcnt(1)
	v_add_f32_e32 v4, v6, v4
	ds_bpermute_b32 v6, v11, v4
	v_cmp_lt_i32_e32 vcc, v13, v2
	s_waitcnt lgkmcnt(1)
	v_add_f32_e32 v3, v3, v5
	v_cndmask_b32_e32 v7, v1, v13, vcc
	v_lshlrev_b32_e32 v12, 2, v7
	s_waitcnt lgkmcnt(0)
	v_add_f32_e32 v4, v4, v6
	ds_bpermute_b32 v5, v12, v3
	ds_bpermute_b32 v6, v12, v4
	v_cmp_lt_i32_e32 vcc, v14, v2
	s_waitcnt lgkmcnt(1)
	v_add_f32_e32 v3, v3, v5
	v_cndmask_b32_e32 v7, v1, v14, vcc
	v_lshlrev_b32_e32 v13, 2, v7
	s_waitcnt lgkmcnt(0)
	v_add_f32_e32 v4, v4, v6
	ds_bpermute_b32 v5, v13, v3
	ds_bpermute_b32 v6, v13, v4
	v_cmp_lt_i32_e32 vcc, v15, v2
	s_waitcnt lgkmcnt(1)
	v_add_f32_e32 v3, v3, v5
	v_cndmask_b32_e32 v7, v1, v15, vcc
	v_lshlrev_b32_e32 v14, 2, v7
	s_waitcnt lgkmcnt(0)
	v_add_f32_e32 v4, v4, v6
	ds_bpermute_b32 v5, v14, v3
	ds_bpermute_b32 v6, v14, v4
	v_cmp_lt_i32_e32 vcc, v16, v2
	s_waitcnt lgkmcnt(1)
	v_add_f32_e32 v3, v3, v5
	v_cndmask_b32_e32 v1, v1, v16, vcc
	v_lshlrev_b32_e32 v15, 2, v1
	s_waitcnt lgkmcnt(0)
	v_add_f32_e32 v1, v4, v6
	ds_bpermute_b32 v4, v15, v3
	ds_bpermute_b32 v2, v15, v1
	s_cbranch_scc1 .LBB0_1039
	s_waitcnt lgkmcnt(1)
	v_add_f32_e32 v4, v3, v4
	s_mov_b32 s6, 0x3fb8aa3b
	v_mul_f32_e32 v3, 0x3fb8aa3b, v4
	v_fma_f32 v5, v4, s6, -v3
	v_rndne_f32_e32 v6, v3
	v_fmac_f32_e32 v5, 0x32a5705f, v4
	v_sub_f32_e32 v3, v3, v6
	v_add_f32_e32 v3, v3, v5
	v_exp_f32_e32 v5, v3
	v_cvt_i32_f32_e32 v6, v6
	s_waitcnt lgkmcnt(0)
	v_add_f32_e32 v1, v1, v2
	v_mul_f32_e32 v2, 0x3fb8aa3b, v1
	v_rndne_f32_e32 v7, v2
	v_ldexp_f32 v5, v5, v6
	v_fma_f32 v6, v1, s6, -v2
	v_fmac_f32_e32 v6, 0x32a5705f, v1
	v_sub_f32_e32 v2, v2, v7
	s_mov_b32 s7, 0xc2ce8ed0
	v_add_f32_e32 v2, v2, v6
	v_cmp_ngt_f32_e32 vcc, s7, v4
	s_mov_b32 s8, 0x42b17218
	v_exp_f32_e32 v2, v2
	v_cvt_i32_f32_e32 v6, v7
	s_add_u32 s2, s0, s2
	v_cndmask_b32_e32 v5, 0, v5, vcc
	v_mov_b32_e32 v7, 0x7f800000
	v_cmp_nlt_f32_e32 vcc, s8, v4
	s_addc_u32 s3, s1, s3
	v_ldexp_f32 v2, v2, v6
	v_cndmask_b32_e32 v4, v7, v5, vcc
	v_cmp_ngt_f32_e32 vcc, s7, v1
	s_load_dwordx2 s[6:7], s[2:3], 0x58
	v_mov_b32_e32 v3, 0
	s_load_dwordx2 s[2:3], s[2:3], 0xc0
	v_cndmask_b32_e32 v2, 0, v2, vcc
	v_cmp_nlt_f32_e32 vcc, s8, v1
	s_ashr_i32 s21, s20, 31
	v_mov_b32_e32 v16, 0x358637bd
	v_cndmask_b32_e32 v1, v7, v2, vcc
	v_lshlrev_b32_e32 v2, 4, v0
	s_waitcnt lgkmcnt(0)
	v_lshl_add_u64 v[6:7], s[6:7], 0, v[2:3]
	s_lshl_b64 s[6:7], s[20:21], 12
	s_add_u32 s2, s2, s6
	v_sub_f32_e32 v1, v4, v1
	v_lshlrev_b32_e32 v2, 3, v0
	s_addc_u32 s3, s3, s7
	v_add_f32_e32 v4, 0x3e4ccccd, v1
	v_lshl_add_u64 v[0:1], s[2:3], 0, v[2:3]
	s_mov_b64 s[2:3], 0x16400600
	s_ashr_i32 s23, s22, 31
	v_mov_b32_e32 v5, v4
	v_lshl_add_u64 v[8:9], v[0:1], 0, s[2:3]
	s_lshl_b64 s[6:7], s[22:23], 12
	s_mov_b32 s8, 0xf800000
	v_mov_b32_e32 v17, 0x260
	s_mov_b32 s9, 0x3f4ccccd
	s_movk_i32 s11, 0x7fff
	s_mov_b32 s12, 0xf0001000
	v_mov_b32_e32 v18, 1
	s_mov_b32 s13, s20
	global_load_dwordx4 v[44:47], v[6:7], off
	global_load_dwordx4 v[48:51], v[6:7], off offset:1024
	global_load_dwordx4 v[52:55], v[6:7], off offset:2048
	global_load_dwordx4 v[56:59], v[6:7], off offset:3072
	v_add_co_u32_e32 v68, vcc, 0xf0000000, v8
	s_nop 1
	v_addc_co_u32_e32 v69, vcc, -1, v9, vcc
	global_load_dwordx2 v[60:61], v[68:69], off offset:-1536
	global_load_dwordx2 v[62:63], v[68:69], off offset:-1024
	global_load_dwordx2 v[64:65], v[68:69], off offset:-512
	global_load_dwordx2 v[66:67], v[68:69], off
	s_waitcnt vmcnt(0)
.LBB0_1038:
	s_add_i32 s13, s13, s22
	s_waitcnt vmcnt(3)
	v_mov_b32_e32 v22, v60
	v_mov_b32_e32 v23, v61
	v_mov_b32_e32 v24, v62
	v_mov_b32_e32 v25, v63
	v_mov_b32_e32 v26, v64
	v_mov_b32_e32 v27, v65
	v_mov_b32_e32 v28, v66
	v_mov_b32_e32 v29, v67
	s_cmpk_lt_i32 s13, 0x4000
	v_lshlrev_b32_e32 v21, 16, v23
	v_lshlrev_b32_e32 v20, 16, v22
	v_lshlrev_b32_e32 v31, 16, v25
	v_lshlrev_b32_e32 v30, 16, v24
	v_and_b32_e32 v23, 0xffff0000, v23
	v_and_b32_e32 v22, 0xffff0000, v22
	v_and_b32_e32 v25, 0xffff0000, v25
	v_and_b32_e32 v24, 0xffff0000, v24
	v_pk_fma_f32 v[22:23], v[4:5], v[24:25], v[22:23] neg_lo:[1,0,0] neg_hi:[1,0,0]
	v_pk_fma_f32 v[20:21], v[4:5], v[30:31], v[20:21] neg_lo:[1,0,0] neg_hi:[1,0,0]
	v_pk_mul_f32 v[24:25], v[22:23], v[22:23]
	v_mov_b32_e32 v0, v44
	v_mov_b32_e32 v1, v45
	v_mov_b32_e32 v2, v46
	v_mov_b32_e32 v3, v47
	v_mov_b32_e32 v34, v0
	v_pk_fma_f32 v[24:25], v[20:21], v[20:21], v[24:25]
	v_mov_b32_e32 v35, v2
	v_add_f32_e32 v19, v24, v25
	v_mov_b32_e32 v2, v1
	v_lshlrev_b32_e32 v37, 16, v27
	v_lshlrev_b32_e32 v39, 16, v29
	v_lshlrev_b32_e32 v38, 16, v28
	s_nop 1
	v_add_f32_dpp v19, v19, v19 quad_perm:[1,0,3,2] row_mask:0xf bank_mask:0xf
	v_and_b32_e32 v27, 0xffff0000, v27
	v_and_b32_e32 v29, 0xffff0000, v29
	v_and_b32_e32 v28, 0xffff0000, v28
	s_nop 1
	v_add_f32_dpp v19, v19, v19 quad_perm:[2,3,0,1] row_mask:0xf bank_mask:0xf
	s_nop 1
	v_add_f32_dpp v19, v19, v19 row_half_mirror row_mask:0xf bank_mask:0xf
	v_add_co_u32_e32 v24, vcc, s12, v8
	s_nop 1
	v_add_f32_dpp v19, v19, v19 row_mirror row_mask:0xf bank_mask:0xf
	v_addc_co_u32_e32 v25, vcc, -1, v9, vcc
	global_load_dwordx2 v[30:31], v[24:25], off offset:-3584
	global_load_dwordx2 v[32:33], v[24:25], off offset:-3072
	s_nop 1
	v_add_f32_dpp v0, v19, v19 row_bcast:15 row_mask:0xa bank_mask:0xf
	v_lshlrev_b32_e32 v36, 16, v26
	v_and_b32_e32 v26, 0xffff0000, v26
	s_nop 1
	v_add_f32_dpp v0, v0, v0 row_bcast:31 row_mask:0xc bank_mask:0xf
	s_nop 0
	v_readlane_b32 s2, v0, 63
	v_mov_b32_e32 v0, s2
	v_fmamk_f32 v0, v0, 0x3b800000, v16
	v_mul_f32_e32 v1, 0x4f800000, v0
	v_cmp_gt_f32_e32 vcc, s8, v0
	s_nop 1
	v_cndmask_b32_e32 v0, v0, v1, vcc
	v_sqrt_f32_e32 v1, v0
	s_nop 0
	v_add_u32_e32 v19, -1, v1
	v_add_u32_e32 v40, 1, v1
	v_fma_f32 v41, -v19, v1, v0
	v_fma_f32 v42, -v40, v1, v0
	v_cmp_ge_f32_e64 s[2:3], 0, v41
	s_nop 1
	v_cndmask_b32_e64 v1, v1, v19, s[2:3]
	v_cmp_lt_f32_e64 s[2:3], 0, v42
	s_nop 1
	v_cndmask_b32_e64 v1, v1, v40, s[2:3]
	v_mul_f32_e32 v19, 0x37800000, v1
	v_cndmask_b32_e32 v1, v1, v19, vcc
	v_cmp_class_f32_e32 vcc, v0, v17
	s_nop 1
	v_cndmask_b32_e32 v0, v1, v0, vcc
	v_div_scale_f32 v1, s[2:3], v0, v0, s9
	v_rcp_f32_e32 v19, v1
	v_div_scale_f32 v40, vcc, s9, v0, s9
	v_fma_f32 v41, -v1, v19, 1.0
	v_fmac_f32_e32 v19, v41, v19
	v_mul_f32_e32 v41, v40, v19
	v_fma_f32 v42, -v1, v41, v40
	v_fmac_f32_e32 v41, v42, v19
	v_fma_f32 v1, -v1, v41, v40
	v_div_fmas_f32 v1, v1, v19, v41
	v_div_fixup_f32 v0, v1, v0, s9
	v_pk_mul_f32 v[20:21], v[20:21], v[0:1] op_sel_hi:[1,0]
	v_pk_mul_f32 v[0:1], v[22:23], v[0:1] op_sel_hi:[1,0]
	v_pk_mul_f32 v[20:21], v[34:35], v[20:21]
	v_pk_mul_f32 v[0:1], v[2:3], v[0:1]
	v_and_b32_sdwa v2, v21, v18 dst_sel:DWORD dst_unused:UNUSED_PAD src0_sel:WORD_1 src1_sel:DWORD
	v_and_b32_sdwa v19, v1, v18 dst_sel:DWORD dst_unused:UNUSED_PAD src0_sel:WORD_1 src1_sel:DWORD
	v_and_b32_sdwa v22, v0, v18 dst_sel:DWORD dst_unused:UNUSED_PAD src0_sel:WORD_1 src1_sel:DWORD
	v_and_b32_sdwa v3, v20, v18 dst_sel:DWORD dst_unused:UNUSED_PAD src0_sel:WORD_1 src1_sel:DWORD
	v_add3_u32 v1, v1, v19, s11
	v_add3_u32 v0, v0, v22, s11
	v_add3_u32 v3, v20, v3, s11
	v_add3_u32 v2, v21, v2, s11
	v_and_b32_e32 v1, 0xffff0000, v1
	v_and_b32_e32 v0, 0xffff0000, v0
	v_or_b32_sdwa v1, v1, v2 dst_sel:DWORD dst_unused:UNUSED_PAD src0_sel:DWORD src1_sel:WORD_1
	v_or_b32_sdwa v0, v0, v3 dst_sel:DWORD dst_unused:UNUSED_PAD src0_sel:DWORD src1_sel:WORD_1
	global_store_dwordx2 v[8:9], v[0:1], off offset:-1536
	v_pk_fma_f32 v[22:23], v[4:5], v[28:29], v[26:27] neg_lo:[1,0,0] neg_hi:[1,0,0]
	v_pk_fma_f32 v[20:21], v[4:5], v[38:39], v[36:37] neg_lo:[1,0,0] neg_hi:[1,0,0]
	v_pk_mul_f32 v[26:27], v[22:23], v[22:23]
	s_waitcnt vmcnt(1)
	v_lshlrev_b32_e32 v35, 16, v33
	v_pk_fma_f32 v[26:27], v[20:21], v[20:21], v[26:27]
	v_and_b32_e32 v33, 0xffff0000, v33
	v_add_f32_e32 v19, v26, v27
	s_nop 1
	v_add_f32_dpp v19, v19, v19 quad_perm:[1,0,3,2] row_mask:0xf bank_mask:0xf
	s_nop 1
	v_add_f32_dpp v19, v19, v19 quad_perm:[2,3,0,1] row_mask:0xf bank_mask:0xf
	s_nop 1
	v_add_f32_dpp v19, v19, v19 row_half_mirror row_mask:0xf bank_mask:0xf
	s_nop 1
	v_add_f32_dpp v19, v19, v19 row_mirror row_mask:0xf bank_mask:0xf
	s_nop 1
	v_add_f32_dpp v19, v19, v19 row_bcast:15 row_mask:0xa bank_mask:0xf
	global_load_dwordx2 v[26:27], v[24:25], off offset:-2560
	global_load_dwordx2 v[28:29], v[24:25], off offset:-2048
	s_cbranch_scc0 .Lp7_nopf
	v_lshl_add_u64 v[68:69], v[8:9], 0, s[6:7]
	s_nop 0
	v_add_co_u32_e32 v68, vcc, 0xf0000000, v68
	s_nop 1
	v_addc_co_u32_e32 v69, vcc, -1, v69, vcc
	global_load_dwordx2 v[60:61], v[68:69], off offset:-1536
	global_load_dwordx2 v[62:63], v[68:69], off offset:-1024
	global_load_dwordx2 v[64:65], v[68:69], off offset:-512
	global_load_dwordx2 v[66:67], v[68:69], off
.Lp7_nopf:
	v_lshlrev_b32_e32 v25, 16, v31
	v_lshlrev_b32_e32 v24, 16, v30
	v_and_b32_e32 v31, 0xffff0000, v31
	s_nop 1
	v_add_f32_dpp v19, v19, v19 row_bcast:31 row_mask:0xc bank_mask:0xf
	s_nop 0
	v_readlane_b32 s2, v19, 63
	v_mov_b32_e32 v19, s2
	v_fmamk_f32 v19, v19, 0x3b800000, v16
	v_mul_f32_e32 v34, 0x4f800000, v19
	v_cmp_gt_f32_e32 vcc, s8, v19
	v_and_b32_e32 v30, 0xffff0000, v30
	s_nop 0
	v_cndmask_b32_e32 v19, v19, v34, vcc
	v_sqrt_f32_e32 v36, v19
	v_lshlrev_b32_e32 v34, 16, v32
	v_and_b32_e32 v32, 0xffff0000, v32
	v_add_u32_e32 v37, -1, v36
	v_add_u32_e32 v38, 1, v36
	v_fma_f32 v39, -v37, v36, v19
	v_fma_f32 v40, -v38, v36, v19
	v_cmp_ge_f32_e64 s[2:3], 0, v39
	s_nop 1
	v_cndmask_b32_e64 v36, v36, v37, s[2:3]
	v_cmp_lt_f32_e64 s[2:3], 0, v40
	s_nop 1
	v_cndmask_b32_e64 v36, v36, v38, s[2:3]
	v_mul_f32_e32 v37, 0x37800000, v36
	v_cndmask_b32_e32 v36, v36, v37, vcc
	v_cmp_class_f32_e32 vcc, v19, v17
	s_nop 1
	v_cndmask_b32_e32 v19, v36, v19, vcc
	v_div_scale_f32 v36, s[2:3], v19, v19, s9
	v_rcp_f32_e32 v37, v36
	v_div_scale_f32 v38, vcc, s9, v19, s9
	v_fma_f32 v39, -v36, v37, 1.0
	v_fmac_f32_e32 v37, v39, v37
	v_mul_f32_e32 v39, v38, v37
	v_fma_f32 v40, -v36, v39, v38
	v_fmac_f32_e32 v39, v40, v37
	v_fma_f32 v36, -v36, v39, v38
	v_div_fmas_f32 v36, v36, v37, v39
	v_div_fixup_f32 v36, v36, v19, s9
	v_pk_mul_f32 v[20:21], v[20:21], v[36:37] op_sel_hi:[1,0]
	v_pk_mul_f32 v[22:23], v[22:23], v[36:37] op_sel_hi:[1,0]
	v_mov_b32_e32 v0, v48
	v_mov_b32_e32 v1, v49
	v_mov_b32_e32 v2, v50
	v_mov_b32_e32 v3, v51
	v_mov_b32_e32 v37, v2
	v_mov_b32_e32 v2, v1
	v_mov_b32_e32 v36, v0
	v_pk_mul_f32 v[2:3], v[2:3], v[22:23]
	v_pk_mul_f32 v[0:1], v[36:37], v[20:21]
	v_and_b32_sdwa v21, v3, v18 dst_sel:DWORD dst_unused:UNUSED_PAD src0_sel:WORD_1 src1_sel:DWORD
	v_and_b32_sdwa v22, v2, v18 dst_sel:DWORD dst_unused:UNUSED_PAD src0_sel:WORD_1 src1_sel:DWORD
	v_and_b32_sdwa v19, v1, v18 dst_sel:DWORD dst_unused:UNUSED_PAD src0_sel:WORD_1 src1_sel:DWORD
	v_and_b32_sdwa v20, v0, v18 dst_sel:DWORD dst_unused:UNUSED_PAD src0_sel:WORD_1 src1_sel:DWORD
	v_add3_u32 v3, v3, v21, s11
	v_add3_u32 v2, v2, v22, s11
	v_add3_u32 v0, v0, v20, s11
	v_add3_u32 v1, v1, v19, s11
	v_and_b32_e32 v3, 0xffff0000, v3
	v_and_b32_e32 v2, 0xffff0000, v2
	v_or_b32_sdwa v1, v3, v1 dst_sel:DWORD dst_unused:UNUSED_PAD src0_sel:DWORD src1_sel:WORD_1
	v_or_b32_sdwa v0, v2, v0 dst_sel:DWORD dst_unused:UNUSED_PAD src0_sel:DWORD src1_sel:WORD_1
	global_store_dwordx2 v[8:9], v[0:1], off offset:-1024
	v_pk_fma_f32 v[22:23], v[4:5], v[32:33], v[30:31] neg_lo:[1,0,0] neg_hi:[1,0,0]
	v_pk_fma_f32 v[20:21], v[4:5], v[34:35], v[24:25] neg_lo:[1,0,0] neg_hi:[1,0,0]
	v_pk_mul_f32 v[24:25], v[22:23], v[22:23]
	s_cbranch_scc0 .Lp7_w1
	s_waitcnt vmcnt(5)
	s_branch .Lp7_wd
.Lp7_w1:
	s_waitcnt vmcnt(1)
.Lp7_wd:
	v_lshlrev_b32_e32 v31, 16, v29
	v_pk_fma_f32 v[24:25], v[20:21], v[20:21], v[24:25]
	v_and_b32_e32 v29, 0xffff0000, v29
	v_add_f32_e32 v19, v24, v25
	v_lshlrev_b32_e32 v25, 16, v27
	v_and_b32_e32 v27, 0xffff0000, v27
	s_nop 1
	v_add_f32_dpp v19, v19, v19 quad_perm:[1,0,3,2] row_mask:0xf bank_mask:0xf
	s_nop 1
	v_add_f32_dpp v19, v19, v19 quad_perm:[2,3,0,1] row_mask:0xf bank_mask:0xf
	s_nop 1
	v_add_f32_dpp v19, v19, v19 row_half_mirror row_mask:0xf bank_mask:0xf
	s_nop 1
	v_add_f32_dpp v19, v19, v19 row_mirror row_mask:0xf bank_mask:0xf
	s_nop 1
	v_add_f32_dpp v19, v19, v19 row_bcast:15 row_mask:0xa bank_mask:0xf
	v_lshlrev_b32_e32 v24, 16, v26
	v_and_b32_e32 v26, 0xffff0000, v26
	s_nop 1
	v_add_f32_dpp v19, v19, v19 row_bcast:31 row_mask:0xc bank_mask:0xf
	s_nop 0
	v_readlane_b32 s2, v19, 63
	v_mov_b32_e32 v19, s2
	v_fmamk_f32 v19, v19, 0x3b800000, v16
	v_mul_f32_e32 v30, 0x4f800000, v19
	v_cmp_gt_f32_e32 vcc, s8, v19
	s_nop 1
	v_cndmask_b32_e32 v19, v19, v30, vcc
	v_sqrt_f32_e32 v32, v19
	v_lshlrev_b32_e32 v30, 16, v28
	v_and_b32_e32 v28, 0xffff0000, v28
	v_add_u32_e32 v33, -1, v32
	v_add_u32_e32 v34, 1, v32
	v_fma_f32 v35, -v33, v32, v19
	v_fma_f32 v36, -v34, v32, v19
	v_cmp_ge_f32_e64 s[2:3], 0, v35
	s_nop 1
	v_cndmask_b32_e64 v32, v32, v33, s[2:3]
	v_cmp_lt_f32_e64 s[2:3], 0, v36
	s_nop 1
	v_cndmask_b32_e64 v32, v32, v34, s[2:3]
	v_mul_f32_e32 v33, 0x37800000, v32
	v_cndmask_b32_e32 v32, v32, v33, vcc
	v_cmp_class_f32_e32 vcc, v19, v17
	s_nop 1
	v_cndmask_b32_e32 v19, v32, v19, vcc
	v_div_scale_f32 v32, s[2:3], v19, v19, s9
	v_rcp_f32_e32 v33, v32
	v_div_scale_f32 v34, vcc, s9, v19, s9
	v_fma_f32 v35, -v32, v33, 1.0
	v_fmac_f32_e32 v33, v35, v33
	v_mul_f32_e32 v35, v34, v33
	v_fma_f32 v36, -v32, v35, v34
	v_fmac_f32_e32 v35, v36, v33
	v_fma_f32 v32, -v32, v35, v34
	v_div_fmas_f32 v32, v32, v33, v35
	v_div_fixup_f32 v32, v32, v19, s9
	v_pk_mul_f32 v[20:21], v[20:21], v[32:33] op_sel_hi:[1,0]
	v_pk_mul_f32 v[22:23], v[22:23], v[32:33] op_sel_hi:[1,0]
	v_mov_b32_e32 v0, v52
	v_mov_b32_e32 v1, v53
	v_mov_b32_e32 v2, v54
	v_mov_b32_e32 v3, v55
	v_mov_b32_e32 v33, v2
	v_mov_b32_e32 v2, v1
	v_mov_b32_e32 v32, v0
	v_pk_mul_f32 v[2:3], v[2:3], v[22:23]
	v_pk_mul_f32 v[0:1], v[32:33], v[20:21]
	v_and_b32_sdwa v21, v3, v18 dst_sel:DWORD dst_unused:UNUSED_PAD src0_sel:WORD_1 src1_sel:DWORD
	v_and_b32_sdwa v22, v2, v18 dst_sel:DWORD dst_unused:UNUSED_PAD src0_sel:WORD_1 src1_sel:DWORD
	v_and_b32_sdwa v19, v1, v18 dst_sel:DWORD dst_unused:UNUSED_PAD src0_sel:WORD_1 src1_sel:DWORD
	v_and_b32_sdwa v20, v0, v18 dst_sel:DWORD dst_unused:UNUSED_PAD src0_sel:WORD_1 src1_sel:DWORD
	v_add3_u32 v3, v3, v21, s11
	v_add3_u32 v2, v2, v22, s11
	v_add3_u32 v0, v0, v20, s11
	v_add3_u32 v1, v1, v19, s11
	v_and_b32_e32 v3, 0xffff0000, v3
	v_and_b32_e32 v2, 0xffff0000, v2
	v_or_b32_sdwa v1, v3, v1 dst_sel:DWORD dst_unused:UNUSED_PAD src0_sel:DWORD src1_sel:WORD_1
	v_or_b32_sdwa v0, v2, v0 dst_sel:DWORD dst_unused:UNUSED_PAD src0_sel:DWORD src1_sel:WORD_1
	global_store_dwordx2 v[8:9], v[0:1], off offset:-512
	v_pk_fma_f32 v[22:23], v[4:5], v[28:29], v[26:27] neg_lo:[1,0,0] neg_hi:[1,0,0]
	v_pk_fma_f32 v[20:21], v[4:5], v[30:31], v[24:25] neg_lo:[1,0,0] neg_hi:[1,0,0]
	v_pk_mul_f32 v[24:25], v[22:23], v[22:23]
	s_nop 0
	v_pk_fma_f32 v[24:25], v[20:21], v[20:21], v[24:25]
	s_nop 0
	v_add_f32_e32 v19, v24, v25
	s_nop 1
	v_add_f32_dpp v19, v19, v19 quad_perm:[1,0,3,2] row_mask:0xf bank_mask:0xf
	s_nop 1
	v_add_f32_dpp v19, v19, v19 quad_perm:[2,3,0,1] row_mask:0xf bank_mask:0xf
	s_nop 1
	v_add_f32_dpp v19, v19, v19 row_half_mirror row_mask:0xf bank_mask:0xf
	s_nop 1
	v_add_f32_dpp v19, v19, v19 row_mirror row_mask:0xf bank_mask:0xf
	s_nop 1
	v_add_f32_dpp v19, v19, v19 row_bcast:15 row_mask:0xa bank_mask:0xf
	s_nop 1
	v_add_f32_dpp v19, v19, v19 row_bcast:31 row_mask:0xc bank_mask:0xf
	s_nop 0
	v_readlane_b32 s2, v19, 63
	v_mov_b32_e32 v19, s2
	v_fmamk_f32 v19, v19, 0x3b800000, v16
	v_mul_f32_e32 v24, 0x4f800000, v19
	v_cmp_gt_f32_e32 vcc, s8, v19
	s_nop 1
	v_cndmask_b32_e32 v19, v19, v24, vcc
	v_sqrt_f32_e32 v24, v19
	s_nop 0
	v_add_u32_e32 v25, -1, v24
	v_add_u32_e32 v26, 1, v24
	v_fma_f32 v27, -v25, v24, v19
	v_fma_f32 v28, -v26, v24, v19
	v_cmp_ge_f32_e64 s[2:3], 0, v27
	s_nop 1
	v_cndmask_b32_e64 v24, v24, v25, s[2:3]
	v_cmp_lt_f32_e64 s[2:3], 0, v28
	s_nop 1
	v_cndmask_b32_e64 v24, v24, v26, s[2:3]
	v_mul_f32_e32 v25, 0x37800000, v24
	v_cndmask_b32_e32 v24, v24, v25, vcc
	v_cmp_class_f32_e32 vcc, v19, v17
	s_nop 1
	v_cndmask_b32_e32 v19, v24, v19, vcc
	v_div_scale_f32 v24, s[2:3], v19, v19, s9
	v_rcp_f32_e32 v25, v24
	v_div_scale_f32 v26, vcc, s9, v19, s9
	v_fma_f32 v27, -v24, v25, 1.0
	v_fmac_f32_e32 v25, v27, v25
	v_mul_f32_e32 v27, v26, v25
	v_fma_f32 v28, -v24, v27, v26
	v_fmac_f32_e32 v27, v28, v25
	v_fma_f32 v24, -v24, v27, v26
	v_div_fmas_f32 v24, v24, v25, v27
	v_div_fixup_f32 v24, v24, v19, s9
	v_pk_mul_f32 v[20:21], v[20:21], v[24:25] op_sel_hi:[1,0]
	v_pk_mul_f32 v[22:23], v[22:23], v[24:25] op_sel_hi:[1,0]
	v_mov_b32_e32 v0, v56
	v_mov_b32_e32 v1, v57
	v_mov_b32_e32 v2, v58
	v_mov_b32_e32 v3, v59
	v_mov_b32_e32 v25, v2
	v_mov_b32_e32 v2, v1
	v_mov_b32_e32 v24, v0
	v_pk_mul_f32 v[2:3], v[2:3], v[22:23]
	v_pk_mul_f32 v[0:1], v[24:25], v[20:21]
	v_and_b32_sdwa v21, v3, v18 dst_sel:DWORD dst_unused:UNUSED_PAD src0_sel:WORD_1 src1_sel:DWORD
	v_and_b32_sdwa v22, v2, v18 dst_sel:DWORD dst_unused:UNUSED_PAD src0_sel:WORD_1 src1_sel:DWORD
	v_and_b32_sdwa v19, v1, v18 dst_sel:DWORD dst_unused:UNUSED_PAD src0_sel:WORD_1 src1_sel:DWORD
	v_and_b32_sdwa v20, v0, v18 dst_sel:DWORD dst_unused:UNUSED_PAD src0_sel:WORD_1 src1_sel:DWORD
	v_add3_u32 v3, v3, v21, s11
	v_add3_u32 v2, v2, v22, s11
	v_add3_u32 v0, v0, v20, s11
	v_add3_u32 v1, v1, v19, s11
	v_and_b32_e32 v3, 0xffff0000, v3
	v_and_b32_e32 v2, 0xffff0000, v2
	v_or_b32_sdwa v1, v3, v1 dst_sel:DWORD dst_unused:UNUSED_PAD src0_sel:DWORD src1_sel:WORD_1
	v_or_b32_sdwa v0, v2, v0 dst_sel:DWORD dst_unused:UNUSED_PAD src0_sel:DWORD src1_sel:WORD_1
	global_store_dwordx2 v[8:9], v[0:1], off
	v_lshl_add_u64 v[8:9], v[8:9], 0, s[6:7]
	s_cbranch_scc1 .LBB0_1038
